# per-tile accumulator zeroing with 64 v_mov_b64 instead of 128 v_mov_b32 in the 8 GEMM sites
# baseline (speedup 1.0000x reference)
; template <class EpiT>
; __device__ __forceinline__ void gemm_phase(LAS unsigned char* lds, const Gemm g, const StaticOrder& S, const EpiT& E) {
;     ...
; #pragma unroll
;         for (int a = 0; a < 2; ++a)
; #pragma unroll
;             for (int b = 0; b < 2; ++b)
; #pragma unroll
;                 for (int m = 0; m < 4; ++m)
; #pragma unroll
;                     for (int n = 0; n < 2; ++n) acc[a][b][m][n] = (f32x4){0.f, 0.f, 0.f, 0.f};
;         cur = nxt; cA = nA; cB = nB; ++ui;
.LBB0_99:
	s_add_u32 s16, s16, 0x84080
	s_addc_u32 s17, s17, 0
	s_add_u32 s51, s18, 0x100
	s_addc_u32 s52, s19, 0
	s_mov_b32 s53, -2
	v_mov_b64_e32 v[0:1], 0
	v_mov_b64_e32 v[2:3], 0
	v_mov_b64_e32 v[4:5], 0
	v_mov_b64_e32 v[6:7], 0
	v_mov_b64_e32 v[16:17], 0
	v_mov_b64_e32 v[18:19], 0
	v_mov_b64_e32 v[20:21], 0
	v_mov_b64_e32 v[22:23], 0
	v_mov_b64_e32 v[32:33], 0
	v_mov_b64_e32 v[34:35], 0
	v_mov_b64_e32 v[36:37], 0
	v_mov_b64_e32 v[38:39], 0
	v_mov_b64_e32 v[48:49], 0
	v_mov_b64_e32 v[50:51], 0
	v_mov_b64_e32 v[52:53], 0
	v_mov_b64_e32 v[54:55], 0
	v_mov_b64_e32 v[8:9], 0
	v_mov_b64_e32 v[10:11], 0
	v_mov_b64_e32 v[12:13], 0
	v_mov_b64_e32 v[14:15], 0
	v_mov_b64_e32 v[24:25], 0
	v_mov_b64_e32 v[26:27], 0
	v_mov_b64_e32 v[28:29], 0
	v_mov_b64_e32 v[30:31], 0
	v_mov_b64_e32 v[40:41], 0
	v_mov_b64_e32 v[42:43], 0
	v_mov_b64_e32 v[44:45], 0
	v_mov_b64_e32 v[46:47], 0
	v_mov_b64_e32 v[56:57], 0
	v_mov_b64_e32 v[58:59], 0
	v_mov_b64_e32 v[60:61], 0
	v_mov_b64_e32 v[62:63], 0
	v_mov_b64_e32 v[64:65], 0
	v_mov_b64_e32 v[66:67], 0
	v_mov_b64_e32 v[68:69], 0
	v_mov_b64_e32 v[70:71], 0
	v_mov_b64_e32 v[80:81], 0
	v_mov_b64_e32 v[82:83], 0
	v_mov_b64_e32 v[84:85], 0
	v_mov_b64_e32 v[86:87], 0
	v_mov_b64_e32 v[96:97], 0
	v_mov_b64_e32 v[98:99], 0
	v_mov_b64_e32 v[100:101], 0
	v_mov_b64_e32 v[102:103], 0
	v_mov_b64_e32 v[112:113], 0
	v_mov_b64_e32 v[114:115], 0
	v_mov_b64_e32 v[116:117], 0
	v_mov_b64_e32 v[118:119], 0
	v_mov_b64_e32 v[72:73], 0
	v_mov_b64_e32 v[74:75], 0
	v_mov_b64_e32 v[76:77], 0
	v_mov_b64_e32 v[78:79], 0
	v_mov_b64_e32 v[88:89], 0
	v_mov_b64_e32 v[90:91], 0
	v_mov_b64_e32 v[92:93], 0
	v_mov_b64_e32 v[94:95], 0
	v_mov_b64_e32 v[104:105], 0
	v_mov_b64_e32 v[106:107], 0
	v_mov_b64_e32 v[108:109], 0
	v_mov_b64_e32 v[110:111], 0
	v_mov_b64_e32 v[120:121], 0
	v_mov_b64_e32 v[122:123], 0
	v_mov_b64_e32 v[124:125], 0
	v_mov_b64_e32 v[126:127], 0

; template <class EpiT>
; __device__ __forceinline__ void gemm_phase(LAS unsigned char* lds, const Gemm g, const StaticOrder& S, const EpiT& E) {
;     ...
; #pragma unroll
;         for (int a = 0; a < 2; ++a)
; #pragma unroll
;             for (int b = 0; b < 2; ++b)
; #pragma unroll
;                 for (int m = 0; m < 4; ++m)
; #pragma unroll
;                     for (int n = 0; n < 2; ++n) acc[a][b][m][n] = (f32x4){0.f, 0.f, 0.f, 0.f};
;         cur = nxt; cA = nA; cB = nB; ++ui;
.LBB0_391:
	s_add_u32 s18, s18, 0x84080
	s_addc_u32 s19, s19, 0
	s_add_u32 s51, s20, 0x100
	s_addc_u32 s52, s21, 0
	s_mov_b32 s53, -2
	v_mov_b64_e32 v[0:1], 0
	v_mov_b64_e32 v[2:3], 0
	v_mov_b64_e32 v[4:5], 0
	v_mov_b64_e32 v[6:7], 0
	v_mov_b64_e32 v[16:17], 0
	v_mov_b64_e32 v[18:19], 0
	v_mov_b64_e32 v[20:21], 0
	v_mov_b64_e32 v[22:23], 0
	v_mov_b64_e32 v[32:33], 0
	v_mov_b64_e32 v[34:35], 0
	v_mov_b64_e32 v[36:37], 0
	v_mov_b64_e32 v[38:39], 0
	v_mov_b64_e32 v[48:49], 0
	v_mov_b64_e32 v[50:51], 0
	v_mov_b64_e32 v[52:53], 0
	v_mov_b64_e32 v[54:55], 0
	v_mov_b64_e32 v[8:9], 0
	v_mov_b64_e32 v[10:11], 0
	v_mov_b64_e32 v[12:13], 0
	v_mov_b64_e32 v[14:15], 0
	v_mov_b64_e32 v[24:25], 0
	v_mov_b64_e32 v[26:27], 0
	v_mov_b64_e32 v[28:29], 0
	v_mov_b64_e32 v[30:31], 0
	v_mov_b64_e32 v[40:41], 0
	v_mov_b64_e32 v[42:43], 0
	v_mov_b64_e32 v[44:45], 0
	v_mov_b64_e32 v[46:47], 0
	v_mov_b64_e32 v[56:57], 0
	v_mov_b64_e32 v[58:59], 0
	v_mov_b64_e32 v[60:61], 0
	v_mov_b64_e32 v[62:63], 0
	v_mov_b64_e32 v[64:65], 0
	v_mov_b64_e32 v[66:67], 0
	v_mov_b64_e32 v[68:69], 0
	v_mov_b64_e32 v[70:71], 0
	v_mov_b64_e32 v[80:81], 0
	v_mov_b64_e32 v[82:83], 0
	v_mov_b64_e32 v[84:85], 0
	v_mov_b64_e32 v[86:87], 0
	v_mov_b64_e32 v[96:97], 0
	v_mov_b64_e32 v[98:99], 0
	v_mov_b64_e32 v[100:101], 0
	v_mov_b64_e32 v[102:103], 0
	v_mov_b64_e32 v[112:113], 0
	v_mov_b64_e32 v[114:115], 0
	v_mov_b64_e32 v[116:117], 0
	v_mov_b64_e32 v[118:119], 0
	v_mov_b64_e32 v[72:73], 0
	v_mov_b64_e32 v[74:75], 0
	v_mov_b64_e32 v[76:77], 0
	v_mov_b64_e32 v[78:79], 0
	v_mov_b64_e32 v[88:89], 0
	v_mov_b64_e32 v[90:91], 0
	v_mov_b64_e32 v[92:93], 0
	v_mov_b64_e32 v[94:95], 0
	v_mov_b64_e32 v[104:105], 0
	v_mov_b64_e32 v[106:107], 0
	v_mov_b64_e32 v[108:109], 0
	v_mov_b64_e32 v[110:111], 0
	v_mov_b64_e32 v[120:121], 0
	v_mov_b64_e32 v[122:123], 0
	v_mov_b64_e32 v[124:125], 0
	v_mov_b64_e32 v[126:127], 0

; template <class EpiT>
; __device__ __forceinline__ void gemm_phase(LAS unsigned char* lds, const Gemm g, const StaticOrder& S, const EpiT& E) {
;     ...
; #pragma unroll
;         for (int a = 0; a < 2; ++a)
; #pragma unroll
;             for (int b = 0; b < 2; ++b)
; #pragma unroll
;                 for (int m = 0; m < 4; ++m)
; #pragma unroll
;                     for (int n = 0; n < 2; ++n) acc[a][b][m][n] = (f32x4){0.f, 0.f, 0.f, 0.f};
;         cur = nxt; cA = nA; cB = nB; ++ui;
.LBB0_594:
	s_add_u32 s18, s18, 0x164080
	s_addc_u32 s19, s19, 0
	s_add_u32 s53, s20, 0x100
	s_addc_u32 s54, s21, 0
	s_mov_b32 s55, -2
	v_mov_b64_e32 v[0:1], 0
	v_mov_b64_e32 v[2:3], 0
	v_mov_b64_e32 v[4:5], 0
	v_mov_b64_e32 v[6:7], 0
	v_mov_b64_e32 v[16:17], 0
	v_mov_b64_e32 v[18:19], 0
	v_mov_b64_e32 v[20:21], 0
	v_mov_b64_e32 v[22:23], 0
	v_mov_b64_e32 v[32:33], 0
	v_mov_b64_e32 v[34:35], 0
	v_mov_b64_e32 v[36:37], 0
	v_mov_b64_e32 v[38:39], 0
	v_mov_b64_e32 v[48:49], 0
	v_mov_b64_e32 v[50:51], 0
	v_mov_b64_e32 v[52:53], 0
	v_mov_b64_e32 v[54:55], 0
	v_mov_b64_e32 v[8:9], 0
	v_mov_b64_e32 v[10:11], 0
	v_mov_b64_e32 v[12:13], 0
	v_mov_b64_e32 v[14:15], 0
	v_mov_b64_e32 v[24:25], 0
	v_mov_b64_e32 v[26:27], 0
	v_mov_b64_e32 v[28:29], 0
	v_mov_b64_e32 v[30:31], 0
	v_mov_b64_e32 v[40:41], 0
	v_mov_b64_e32 v[42:43], 0
	v_mov_b64_e32 v[44:45], 0
	v_mov_b64_e32 v[46:47], 0
	v_mov_b64_e32 v[56:57], 0
	v_mov_b64_e32 v[58:59], 0
	v_mov_b64_e32 v[60:61], 0
	v_mov_b64_e32 v[62:63], 0
	v_mov_b64_e32 v[64:65], 0
	v_mov_b64_e32 v[66:67], 0
	v_mov_b64_e32 v[68:69], 0
	v_mov_b64_e32 v[70:71], 0
	v_mov_b64_e32 v[80:81], 0
	v_mov_b64_e32 v[82:83], 0
	v_mov_b64_e32 v[84:85], 0
	v_mov_b64_e32 v[86:87], 0
	v_mov_b64_e32 v[96:97], 0
	v_mov_b64_e32 v[98:99], 0
	v_mov_b64_e32 v[100:101], 0
	v_mov_b64_e32 v[102:103], 0
	v_mov_b64_e32 v[112:113], 0
	v_mov_b64_e32 v[114:115], 0
	v_mov_b64_e32 v[116:117], 0
	v_mov_b64_e32 v[118:119], 0
	v_mov_b64_e32 v[72:73], 0
	v_mov_b64_e32 v[74:75], 0
	v_mov_b64_e32 v[76:77], 0
	v_mov_b64_e32 v[78:79], 0
	v_mov_b64_e32 v[88:89], 0
	v_mov_b64_e32 v[90:91], 0
	v_mov_b64_e32 v[92:93], 0
	v_mov_b64_e32 v[94:95], 0
	v_mov_b64_e32 v[104:105], 0
	v_mov_b64_e32 v[106:107], 0
	v_mov_b64_e32 v[108:109], 0
	v_mov_b64_e32 v[110:111], 0
	v_mov_b64_e32 v[120:121], 0
	v_mov_b64_e32 v[122:123], 0
	v_mov_b64_e32 v[124:125], 0
	v_mov_b64_e32 v[126:127], 0

; template <class EpiT>
; __device__ __forceinline__ void gemm_phase(LAS unsigned char* lds, const Gemm g, const StaticOrder& S, const EpiT& E) {
;     ...
; #pragma unroll
;         for (int a = 0; a < 2; ++a)
; #pragma unroll
;             for (int b = 0; b < 2; ++b)
; #pragma unroll
;                 for (int m = 0; m < 4; ++m)
; #pragma unroll
;                     for (int n = 0; n < 2; ++n) acc[a][b][m][n] = (f32x4){0.f, 0.f, 0.f, 0.f};
;         cur = nxt; cA = nA; cB = nB; ++ui;
.LBB0_760:
	s_add_u32 s20, s20, 0x84080
	s_addc_u32 s21, s21, 0
	s_add_u32 s8, s22, 0x100
	s_addc_u32 s39, s23, 0
	s_mov_b32 s56, -2
	s_waitcnt lgkmcnt(0)
	v_mov_b64_e32 v[0:1], 0
	v_mov_b64_e32 v[2:3], 0
	v_mov_b64_e32 v[4:5], 0
	v_mov_b64_e32 v[6:7], 0
	v_mov_b64_e32 v[16:17], 0
	v_mov_b64_e32 v[18:19], 0
	v_mov_b64_e32 v[20:21], 0
	v_mov_b64_e32 v[22:23], 0
	v_mov_b64_e32 v[32:33], 0
	v_mov_b64_e32 v[34:35], 0
	v_mov_b64_e32 v[36:37], 0
	v_mov_b64_e32 v[38:39], 0
	v_mov_b64_e32 v[48:49], 0
	v_mov_b64_e32 v[50:51], 0
	v_mov_b64_e32 v[52:53], 0
	v_mov_b64_e32 v[54:55], 0
	v_mov_b64_e32 v[8:9], 0
	v_mov_b64_e32 v[10:11], 0
	v_mov_b64_e32 v[12:13], 0
	v_mov_b64_e32 v[14:15], 0
	v_mov_b64_e32 v[24:25], 0
	v_mov_b64_e32 v[26:27], 0
	v_mov_b64_e32 v[28:29], 0
	v_mov_b64_e32 v[30:31], 0
	v_mov_b64_e32 v[40:41], 0
	v_mov_b64_e32 v[42:43], 0
	v_mov_b64_e32 v[44:45], 0
	v_mov_b64_e32 v[46:47], 0
	v_mov_b64_e32 v[56:57], 0
	v_mov_b64_e32 v[58:59], 0
	v_mov_b64_e32 v[60:61], 0
	v_mov_b64_e32 v[62:63], 0
	v_mov_b64_e32 v[64:65], 0
	v_mov_b64_e32 v[66:67], 0
	v_mov_b64_e32 v[68:69], 0
	v_mov_b64_e32 v[70:71], 0
	v_mov_b64_e32 v[80:81], 0
	v_mov_b64_e32 v[82:83], 0
	v_mov_b64_e32 v[84:85], 0
	v_mov_b64_e32 v[86:87], 0
	v_mov_b64_e32 v[96:97], 0
	v_mov_b64_e32 v[98:99], 0
	v_mov_b64_e32 v[100:101], 0
	v_mov_b64_e32 v[102:103], 0
	v_mov_b64_e32 v[112:113], 0
	v_mov_b64_e32 v[114:115], 0
	v_mov_b64_e32 v[116:117], 0
	v_mov_b64_e32 v[118:119], 0
	v_mov_b64_e32 v[72:73], 0
	v_mov_b64_e32 v[74:75], 0
	v_mov_b64_e32 v[76:77], 0
	v_mov_b64_e32 v[78:79], 0
	v_mov_b64_e32 v[88:89], 0
	v_mov_b64_e32 v[90:91], 0
	v_mov_b64_e32 v[92:93], 0
	v_mov_b64_e32 v[94:95], 0
	v_mov_b64_e32 v[104:105], 0
	v_mov_b64_e32 v[106:107], 0
	v_mov_b64_e32 v[108:109], 0
	v_mov_b64_e32 v[110:111], 0
	v_mov_b64_e32 v[120:121], 0
	v_mov_b64_e32 v[122:123], 0
	v_mov_b64_e32 v[124:125], 0
	v_mov_b64_e32 v[126:127], 0

; template <class EpiT>
; __device__ __forceinline__ void gemm_phase(LAS unsigned char* lds, const Gemm g, const StaticOrder& S, const EpiT& E) {
;     ...
; #pragma unroll
;         for (int a = 0; a < 2; ++a)
; #pragma unroll
;             for (int b = 0; b < 2; ++b)
; #pragma unroll
;                 for (int m = 0; m < 4; ++m)
; #pragma unroll
;                     for (int n = 0; n < 2; ++n) acc[a][b][m][n] = (f32x4){0.f, 0.f, 0.f, 0.f};
;         cur = nxt; cA = nA; cB = nB; ++ui;
.LBB0_1031:
	s_add_u32 s18, s18, 0x84080
	s_addc_u32 s19, s19, 0
	s_add_u32 s53, s20, 0x100
	s_addc_u32 s54, s21, 0
	s_mov_b32 s55, -2
	v_mov_b64_e32 v[0:1], 0
	v_mov_b64_e32 v[2:3], 0
	v_mov_b64_e32 v[4:5], 0
	v_mov_b64_e32 v[6:7], 0
	v_mov_b64_e32 v[16:17], 0
	v_mov_b64_e32 v[18:19], 0
	v_mov_b64_e32 v[20:21], 0
	v_mov_b64_e32 v[22:23], 0
	v_mov_b64_e32 v[32:33], 0
	v_mov_b64_e32 v[34:35], 0
	v_mov_b64_e32 v[36:37], 0
	v_mov_b64_e32 v[38:39], 0
	v_mov_b64_e32 v[48:49], 0
	v_mov_b64_e32 v[50:51], 0
	v_mov_b64_e32 v[52:53], 0
	v_mov_b64_e32 v[54:55], 0
	v_mov_b64_e32 v[8:9], 0
	v_mov_b64_e32 v[10:11], 0
	v_mov_b64_e32 v[12:13], 0
	v_mov_b64_e32 v[14:15], 0
	v_mov_b64_e32 v[24:25], 0
	v_mov_b64_e32 v[26:27], 0
	v_mov_b64_e32 v[28:29], 0
	v_mov_b64_e32 v[30:31], 0
	v_mov_b64_e32 v[40:41], 0
	v_mov_b64_e32 v[42:43], 0
	v_mov_b64_e32 v[44:45], 0
	v_mov_b64_e32 v[46:47], 0
	v_mov_b64_e32 v[56:57], 0
	v_mov_b64_e32 v[58:59], 0
	v_mov_b64_e32 v[60:61], 0
	v_mov_b64_e32 v[62:63], 0
	v_mov_b64_e32 v[64:65], 0
	v_mov_b64_e32 v[66:67], 0
	v_mov_b64_e32 v[68:69], 0
	v_mov_b64_e32 v[70:71], 0
	v_mov_b64_e32 v[80:81], 0
	v_mov_b64_e32 v[82:83], 0
	v_mov_b64_e32 v[84:85], 0
	v_mov_b64_e32 v[86:87], 0
	v_mov_b64_e32 v[96:97], 0
	v_mov_b64_e32 v[98:99], 0
	v_mov_b64_e32 v[100:101], 0
	v_mov_b64_e32 v[102:103], 0
	v_mov_b64_e32 v[112:113], 0
	v_mov_b64_e32 v[114:115], 0
	v_mov_b64_e32 v[116:117], 0
	v_mov_b64_e32 v[118:119], 0
	v_mov_b64_e32 v[72:73], 0
	v_mov_b64_e32 v[74:75], 0
	v_mov_b64_e32 v[76:77], 0
	v_mov_b64_e32 v[78:79], 0
	v_mov_b64_e32 v[88:89], 0
	v_mov_b64_e32 v[90:91], 0
	v_mov_b64_e32 v[92:93], 0
	v_mov_b64_e32 v[94:95], 0
	v_mov_b64_e32 v[104:105], 0
	v_mov_b64_e32 v[106:107], 0
	v_mov_b64_e32 v[108:109], 0
	v_mov_b64_e32 v[110:111], 0
	v_mov_b64_e32 v[120:121], 0
	v_mov_b64_e32 v[122:123], 0
	v_mov_b64_e32 v[124:125], 0
	v_mov_b64_e32 v[126:127], 0
